# MLA norm+rope row loop: waits that only covered earlier stores removed, rope table loads issued without first draining the data loads, one combined load wait per iteration
# speedup vs baseline: 1.0076x; 1.0050x over previous
; __device__ __forceinline__ void mla_phase(const Params& p, const WsMap& wm, const bf16_t* H, bf16_t* QC, bf16_t* KC, const bf16_t* KV, int Tc, int l) {
;     ...
;     for (int row = gw; row < Tc; row += nw) {
;         const int pos = row & (SEQ - 1);
;         u32x4 w[4];
; #pragma unroll
;         for (int part = 0; part < 4; ++part) {
;             const int isk = part >> 1, h = (part & 1) * 4 + hl;
;             w[part] = (u32x4){0u, 0u, 0u, 0u};
;             if (act) {
;                 if (!isk) w[part] = *(const u32x4*)(QC + (size_t)row * 768 + h * 96 + sub * 8);
;                 else if (sub < 8) w[part] = *(const u32x4*)(KV + (size_t)row * 1024 + h * 128 + sub * 8);
;                 else w[part] = *(const u32x4*)(H + (size_t)row * NP1 + CPE + (sub - 8) * 8);
;             }
;         }
.LBB0_718:
	s_or_b64 exec, exec, s[44:45]
	v_lshl_add_u64 v[14:15], v[64:65], 0, v[54:55]
	v_mov_b32_e32 v10, 0
	v_mov_b32_e32 v30, 0
	v_mov_b32_e32 v31, 0
	v_mov_b32_e32 v32, 0
	v_mov_b32_e32 v33, 0
	s_and_saveexec_b64 s[44:45], s[36:37]
	s_cbranch_execz .LBB0_724
	s_and_saveexec_b64 s[12:13], s[38:39]
	s_xor_b64 s[46:47], exec, s[12:13]
	s_cbranch_execz .LBB0_721
	global_load_dwordx4 v[30:33], v[14:15], off

; __device__ __forceinline__ void mla_phase(const Params& p, const WsMap& wm, const bf16_t* H, bf16_t* QC, bf16_t* KC, const bf16_t* KV, int Tc, int l) {
;     ...
;             if (act) {
;                 if (!isk) w[part] = *(const u32x4*)(QC + (size_t)row * 768 + h * 96 + sub * 8);
;                 else if (sub < 8) w[part] = *(const u32x4*)(KV + (size_t)row * 1024 + h * 128 + sub * 8);
;                 else w[part] = *(const u32x4*)(H + (size_t)row * NP1 + CPE + (sub - 8) * 8);
;             }
.LBB0_727:
	s_andn2_saveexec_b64 s[46:47], s[46:47]
	s_cbranch_execz .LBB0_729
	v_lshl_add_u64 v[86:87], v[62:63], 0, v[54:55]
	v_add_co_u32_e32 v86, vcc, 0xc8ca000, v86
	s_nop 1
	v_addc_co_u32_e32 v87, vcc, 0, v87, vcc
	global_load_dwordx4 v[10:13], v[86:87], off offset:1280

; __device__ __forceinline__ u32x4 pack8(const float (&f)[8]) { u32x4 w; w.x = pk2(f[0], f[1]); w.y = pk2(f[2], f[3]); w.z = pk2(f[4], f[5]); w.w = pk2(f[6], f[7]); return w; }
; __device__ __forceinline__ void mla_phase(const Params& p, const WsMap& wm, const bf16_t* H, bf16_t* QC, bf16_t* KC, const bf16_t* KV, int Tc, int l) {
;     ...
;         const float* cs = rope + pos * 32 + (sub & 1) * 8;
;         const f32x4 c0 = *(const f32x4*)cs, c1 = *(const f32x4*)(cs + 4), s0 = *(const f32x4*)(cs + 16), s1 = *(const f32x4*)(cs + 20);
;         const float cc[8] = {c0[0], c0[1], c0[2], c0[3], c1[0], c1[1], c1[2], c1[3]};
;         const float sn[8] = {s0[0], s0[1], s0[2], s0[3], s1[0], s1[1], s1[2], s1[3]};
; #pragma unroll
;         for (int part = 0; part < 4; ++part) {
;             const int isk = part >> 1, h = (part & 1) * 4 + hl;
;             float f[8]; unpack8(w[part], f); float ss = 0.f;
; #pragma unroll
;             for (int i = 0; i < 8; ++i) ss += f[i] * f[i];
;             ss += __shfl_xor(ss, 1); ss += __shfl_xor(ss, 2); ss += __shfl_xor(ss, 4); ss += __shfl_xor(ss, 8);
;             const float rs = rsqrtf(ss * (1.0f / 96.0f) + 1e-6f);
; #pragma unroll
;             for (int i = 0; i < 8; ++i) f[i] = f[i] * rs * (isk ? gk[i] : gq[i]);
; #pragma unroll
;             for (int i = 0; i < 8; ++i) {
;                 const float other = __shfl_xor(f[i], 2);
;                 if (sub >= 8 && sub < 12) f[i] = (sub < 10) ? (f[i] * cc[i] - other * sn[i]) : (f[i] * cc[i] + other * sn[i]);
;             }
;             if (act) { bf16_t* dst = (isk ? KC : QC) + (size_t)row * 768 + h * 96 + sub * 8; *(u32x4*)dst = pack8(f); }
.LBB0_730:
	s_or_b64 exec, exec, s[44:45]
	s_waitcnt lgkmcnt(0)
	v_and_b32_e32 v0, 0x3ffe0, v76
	v_lshlrev_b32_e32 v0, 2, v0
	v_lshl_add_u64 v[18:19], v[52:53], 0, v[0:1]
	global_load_dwordx4 v[22:25], v[18:19], off
	global_load_dwordx4 v[14:17], v[18:19], off offset:16
	global_load_dwordx4 v[26:29], v[18:19], off offset:64
	s_nop 0
	global_load_dwordx4 v[18:21], v[18:19], off offset:80
	s_waitcnt vmcnt(0)
	v_lshlrev_b32_e32 v68, 16, v38
	v_and_b32_e32 v69, 0xffff0000, v38
	v_pk_mul_f32 v[70:71], v[68:69], v[68:69]
	v_lshlrev_b32_e32 v78, 16, v39
	v_and_b32_e32 v79, 0xffff0000, v39
	v_pk_mul_f32 v[38:39], v[78:79], v[78:79]
	v_add_f32_e32 v0, v70, v71
	v_lshlrev_b32_e32 v80, 16, v40
	v_and_b32_e32 v81, 0xffff0000, v40
	v_add_f32_e32 v0, v38, v0
	v_pk_mul_f32 v[82:83], v[80:81], v[80:81]
	v_add_f32_e32 v0, v39, v0
	v_lshlrev_b32_e32 v84, 16, v41
	v_and_b32_e32 v85, 0xffff0000, v41
	v_add_f32_e32 v0, v82, v0
	v_pk_mul_f32 v[40:41], v[84:85], v[84:85]
	v_add_f32_e32 v0, v83, v0
	v_add_f32_e32 v0, v40, v0
	v_add_f32_e32 v0, v41, v0
	s_nop 1
	v_add_f32_dpp v0, v0, v0 quad_perm:[1,0,3,2] row_mask:0xf bank_mask:0xf
	s_nop 1
	v_add_f32_dpp v0, v0, v0 quad_perm:[2,3,0,1] row_mask:0xf bank_mask:0xf
	s_nop 1
	v_add_f32_dpp v0, v0, v0 row_half_mirror row_mask:0xf bank_mask:0xf
	s_nop 1
	v_add_f32_dpp v0, v0, v0 row_mirror row_mask:0xf bank_mask:0xf
	s_nop 0
	v_fmamk_f32 v0, v0, 0x3c2aaaab, v193
	v_mul_f32_e32 v38, 0x4b800000, v0
	v_cmp_gt_f32_e32 vcc, s68, v0
	s_nop 1
	v_cndmask_b32_e32 v0, v0, v38, vcc
	v_rsq_f32_e32 v0, v0
	s_nop 0
	v_mul_f32_e32 v38, 0x45800000, v0
	v_cndmask_b32_e32 v0, v0, v38, vcc
	v_pk_mul_f32 v[38:39], v[0:1], v[68:69] op_sel_hi:[0,1]
	v_pk_mul_f32 v[68:69], v[0:1], v[80:81] op_sel_hi:[0,1]
	v_pk_mul_f32 v[40:41], v[0:1], v[78:79] op_sel_hi:[0,1]
	v_pk_mul_f32 v[70:71], v[48:49], v[68:69]
	v_pk_mul_f32 v[68:69], v[0:1], v[84:85] op_sel_hi:[0,1]
	v_pk_mul_f32 v[38:39], v[44:45], v[38:39]
	v_pk_mul_f32 v[40:41], v[46:47], v[40:41]
	v_pk_mul_f32 v[68:69], v[50:51], v[68:69]
	s_nop 1
	v_mov_b32_dpp v82, v38 quad_perm:[2,3,0,1] row_mask:0xf bank_mask:0xf
	v_mov_b32_dpp v81, v39 quad_perm:[2,3,0,1] row_mask:0xf bank_mask:0xf
	v_mov_b32_dpp v80, v40 quad_perm:[2,3,0,1] row_mask:0xf bank_mask:0xf
	v_mov_b32_dpp v79, v41 quad_perm:[2,3,0,1] row_mask:0xf bank_mask:0xf
	v_mov_b32_dpp v78, v70 quad_perm:[2,3,0,1] row_mask:0xf bank_mask:0xf
	v_mov_b32_dpp v77, v71 quad_perm:[2,3,0,1] row_mask:0xf bank_mask:0xf
	v_mov_b32_dpp v43, v68 quad_perm:[2,3,0,1] row_mask:0xf bank_mask:0xf
	v_mov_b32_dpp v0, v69 quad_perm:[2,3,0,1] row_mask:0xf bank_mask:0xf
	s_and_saveexec_b64 s[44:45], s[36:37]
	s_cbranch_execz .LBB0_732
	s_waitcnt lgkmcnt(7)
	v_mul_f32_e32 v82, v26, v82
	s_waitcnt lgkmcnt(6)
	v_mul_f32_e32 v81, v27, v81
	s_waitcnt lgkmcnt(5)
	v_mul_f32_e32 v80, v28, v80
	s_waitcnt lgkmcnt(3)
	v_mul_f32_e32 v78, v18, v78
	s_waitcnt lgkmcnt(1)
	v_mul_f32_e32 v43, v20, v43
	v_cndmask_b32_e64 v82, v82, -v82, s[42:43]
	v_cndmask_b32_e64 v81, v81, -v81, s[42:43]
	v_cndmask_b32_e64 v80, v80, -v80, s[42:43]
	v_mul_f32_e32 v79, v29, v79
	v_cndmask_b32_e64 v78, v78, -v78, s[42:43]
	v_mul_f32_e32 v77, v19, v77
	v_cndmask_b32_e64 v43, v43, -v43, s[42:43]
	v_fmac_f32_e32 v82, v22, v38
	v_fmac_f32_e32 v81, v23, v39
	v_fmac_f32_e32 v80, v24, v40
	v_cndmask_b32_e64 v79, v79, -v79, s[42:43]
	v_fmac_f32_e32 v78, v14, v70
	v_cndmask_b32_e64 v77, v77, -v77, s[42:43]
	v_fmac_f32_e32 v43, v16, v68
	v_fmac_f32_e32 v79, v25, v41
	v_fmac_f32_e32 v77, v15, v71
	v_cndmask_b32_e64 v43, v68, v43, s[40:41]
	v_cndmask_b32_e64 v78, v70, v78, s[40:41]
	v_cndmask_b32_e64 v80, v40, v80, s[40:41]
	v_cndmask_b32_e64 v81, v39, v81, s[40:41]
	v_cndmask_b32_e64 v82, v38, v82, s[40:41]
	s_waitcnt lgkmcnt(0)
	v_mul_f32_e32 v0, v21, v0
	v_cndmask_b32_e64 v77, v71, v77, s[40:41]
	v_cndmask_b32_e64 v79, v41, v79, s[40:41]
	v_cndmask_b32_e64 v0, v0, -v0, s[42:43]
	v_cndmask_b32_e64 v43, v68, v43, s[40:41]
	v_cndmask_b32_e64 v68, v70, v78, s[40:41]
	v_cndmask_b32_e64 v40, v40, v80, s[40:41]
	v_cndmask_b32_e64 v38, v38, v82, s[40:41]
	v_cndmask_b32_e64 v39, v39, v81, s[40:41]
	v_fmac_f32_e32 v0, v17, v69
	v_cndmask_b32_e64 v70, v71, v77, s[40:41]
	v_cndmask_b32_e64 v41, v41, v79, s[40:41]
	v_cvt_pk_bf16_f32 v38, v38, v39
	v_cvt_pk_bf16_f32 v39, v40, v41
	v_cvt_pk_bf16_f32 v40, v68, v70
	v_add_co_u32_e32 v68, vcc, 0xc8ca000, v66
	v_cndmask_b32_e64 v0, v69, v0, s[40:41]
	s_nop 0
	v_addc_co_u32_e32 v69, vcc, 0, v67, vcc
	v_cvt_pk_bf16_f32 v41, v43, v0
	global_store_dwordx4 v[68:69], v[38:41], off offset:256
; __device__ __forceinline__ u32x4 pack8(const float (&f)[8]) { u32x4 w; w.x = pk2(f[0], f[1]); w.y = pk2(f[2], f[3]); w.z = pk2(f[4], f[5]); w.w = pk2(f[6], f[7]); return w; }
; __device__ __forceinline__ void mla_phase(const Params& p, const WsMap& wm, const bf16_t* H, bf16_t* QC, bf16_t* KC, const bf16_t* KV, int Tc, int l) {
;     ...
;         for (int part = 0; part < 4; ++part) {
;             const int isk = part >> 1, h = (part & 1) * 4 + hl;
;             float f[8]; unpack8(w[part], f); float ss = 0.f;
; #pragma unroll
;             for (int i = 0; i < 8; ++i) ss += f[i] * f[i];
;             ss += __shfl_xor(ss, 1); ss += __shfl_xor(ss, 2); ss += __shfl_xor(ss, 4); ss += __shfl_xor(ss, 8);
;             const float rs = rsqrtf(ss * (1.0f / 96.0f) + 1e-6f);
; #pragma unroll
;             for (int i = 0; i < 8; ++i) f[i] = f[i] * rs * (isk ? gk[i] : gq[i]);
; #pragma unroll
;             for (int i = 0; i < 8; ++i) {
;                 const float other = __shfl_xor(f[i], 2);
;                 if (sub >= 8 && sub < 12) f[i] = (sub < 10) ? (f[i] * cc[i] - other * sn[i]) : (f[i] * cc[i] + other * sn[i]);
;             }
;             if (act) { bf16_t* dst = (isk ? KC : QC) + (size_t)row * 768 + h * 96 + sub * 8; *(u32x4*)dst = pack8(f); }
.LBB0_732:
	s_or_b64 exec, exec, s[44:45]
	s_nop 0
	v_lshlrev_b32_e32 v38, 16, v34
	v_and_b32_e32 v39, 0xffff0000, v34
	v_pk_mul_f32 v[40:41], v[38:39], v[38:39]
	v_lshlrev_b32_e32 v34, 16, v35
	v_and_b32_e32 v35, 0xffff0000, v35
	v_pk_mul_f32 v[68:69], v[34:35], v[34:35]
	s_waitcnt lgkmcnt(0)
	v_add_f32_e32 v0, v40, v41
	v_lshlrev_b32_e32 v70, 16, v36
	v_and_b32_e32 v71, 0xffff0000, v36
	v_add_f32_e32 v0, v68, v0
	v_pk_mul_f32 v[78:79], v[70:71], v[70:71]
	v_add_f32_e32 v0, v69, v0
	v_lshlrev_b32_e32 v36, 16, v37
	v_and_b32_e32 v37, 0xffff0000, v37
	v_add_f32_e32 v0, v78, v0
	v_pk_mul_f32 v[80:81], v[36:37], v[36:37]
	v_add_f32_e32 v0, v79, v0
	v_add_f32_e32 v0, v80, v0
	v_add_f32_e32 v0, v81, v0
	s_nop 1
	v_add_f32_dpp v0, v0, v0 quad_perm:[1,0,3,2] row_mask:0xf bank_mask:0xf
	s_nop 1
	v_add_f32_dpp v0, v0, v0 quad_perm:[2,3,0,1] row_mask:0xf bank_mask:0xf
	s_nop 1
	v_add_f32_dpp v0, v0, v0 row_half_mirror row_mask:0xf bank_mask:0xf
	s_nop 1
	v_add_f32_dpp v0, v0, v0 row_mirror row_mask:0xf bank_mask:0xf
	s_nop 0
	v_fmamk_f32 v0, v0, 0x3c2aaaab, v193
	v_mul_f32_e32 v40, 0x4b800000, v0
	v_cmp_gt_f32_e32 vcc, s68, v0
	s_nop 1
	v_cndmask_b32_e32 v0, v0, v40, vcc
	v_rsq_f32_e32 v0, v0
	s_nop 0
	v_mul_f32_e32 v40, 0x45800000, v0
	v_cndmask_b32_e32 v0, v0, v40, vcc
	v_pk_mul_f32 v[38:39], v[0:1], v[38:39] op_sel_hi:[0,1]
	v_pk_mul_f32 v[40:41], v[0:1], v[34:35] op_sel_hi:[0,1]
	v_pk_mul_f32 v[68:69], v[0:1], v[70:71] op_sel_hi:[0,1]
	v_pk_mul_f32 v[36:37], v[0:1], v[36:37] op_sel_hi:[0,1]
	v_pk_mul_f32 v[34:35], v[44:45], v[38:39]
	v_pk_mul_f32 v[38:39], v[46:47], v[40:41]
	v_pk_mul_f32 v[40:41], v[48:49], v[68:69]
	v_pk_mul_f32 v[36:37], v[50:51], v[36:37]
	s_nop 1
	v_mov_b32_dpp v78, v34 quad_perm:[2,3,0,1] row_mask:0xf bank_mask:0xf
	v_mov_b32_dpp v77, v35 quad_perm:[2,3,0,1] row_mask:0xf bank_mask:0xf
	v_mov_b32_dpp v71, v38 quad_perm:[2,3,0,1] row_mask:0xf bank_mask:0xf
	v_mov_b32_dpp v70, v39 quad_perm:[2,3,0,1] row_mask:0xf bank_mask:0xf
	v_mov_b32_dpp v69, v40 quad_perm:[2,3,0,1] row_mask:0xf bank_mask:0xf
	v_mov_b32_dpp v68, v41 quad_perm:[2,3,0,1] row_mask:0xf bank_mask:0xf
	v_mov_b32_dpp v43, v36 quad_perm:[2,3,0,1] row_mask:0xf bank_mask:0xf
	v_mov_b32_dpp v0, v37 quad_perm:[2,3,0,1] row_mask:0xf bank_mask:0xf
	s_and_saveexec_b64 s[44:45], s[36:37]
	s_cbranch_execz .LBB0_734
	s_waitcnt lgkmcnt(7)
	v_mul_f32_e32 v78, v26, v78
	s_waitcnt lgkmcnt(6)
	v_mul_f32_e32 v77, v27, v77
	s_waitcnt lgkmcnt(5)
	v_mul_f32_e32 v71, v28, v71
	v_cndmask_b32_e64 v78, v78, -v78, s[42:43]
	v_cndmask_b32_e64 v77, v77, -v77, s[42:43]
	v_cndmask_b32_e64 v71, v71, -v71, s[42:43]
	s_waitcnt lgkmcnt(4)
	v_mul_f32_e32 v70, v29, v70
	v_fmac_f32_e32 v78, v22, v34
	v_fmac_f32_e32 v77, v23, v35
	v_fmac_f32_e32 v71, v24, v38
	v_cndmask_b32_e64 v70, v70, -v70, s[42:43]
	s_waitcnt lgkmcnt(3)
	v_mul_f32_e32 v69, v18, v69
	s_waitcnt lgkmcnt(1)
	v_mul_f32_e32 v43, v20, v43
	v_fmac_f32_e32 v70, v25, v39
	v_cndmask_b32_e64 v69, v69, -v69, s[42:43]
	v_mul_f32_e32 v68, v19, v68
	v_cndmask_b32_e64 v43, v43, -v43, s[42:43]
	v_cndmask_b32_e64 v71, v38, v71, s[40:41]
	v_cndmask_b32_e64 v77, v35, v77, s[40:41]
	v_cndmask_b32_e64 v78, v34, v78, s[40:41]
	v_fmac_f32_e32 v69, v14, v40
	v_cndmask_b32_e64 v68, v68, -v68, s[42:43]
	v_fmac_f32_e32 v43, v16, v36
	v_cndmask_b32_e64 v70, v39, v70, s[40:41]
	s_waitcnt lgkmcnt(0)
	v_mul_f32_e32 v0, v21, v0
	v_cndmask_b32_e64 v38, v38, v71, s[40:41]
	v_cndmask_b32_e64 v34, v34, v78, s[40:41]
	v_cndmask_b32_e64 v35, v35, v77, s[40:41]
	v_fmac_f32_e32 v68, v15, v41
	v_cndmask_b32_e64 v43, v36, v43, s[40:41]
	v_cndmask_b32_e64 v69, v40, v69, s[40:41]
	v_cndmask_b32_e64 v0, v0, -v0, s[42:43]
	v_cndmask_b32_e64 v39, v39, v70, s[40:41]
	v_cvt_pk_bf16_f32 v34, v34, v35
	v_cvt_pk_bf16_f32 v35, v38, v39
	v_add_co_u32_e32 v38, vcc, 0xc8ca000, v66
	v_cndmask_b32_e64 v68, v41, v68, s[40:41]
	v_fmac_f32_e32 v0, v17, v37
	v_cndmask_b32_e64 v43, v36, v43, s[40:41]
	v_cndmask_b32_e64 v36, v40, v69, s[40:41]
	v_addc_co_u32_e32 v39, vcc, 0, v67, vcc
	v_cndmask_b32_e64 v40, v41, v68, s[40:41]
	v_cndmask_b32_e64 v0, v37, v0, s[40:41]
	v_cvt_pk_bf16_f32 v36, v36, v40
	v_cvt_pk_bf16_f32 v37, v43, v0
	global_store_dwordx4 v[38:39], v[34:37], off offset:1024
.LBB0_734:
	s_or_b64 exec, exec, s[44:45]
	s_nop 0
	v_lshlrev_b32_e32 v34, 16, v30
	v_and_b32_e32 v35, 0xffff0000, v30
	v_pk_mul_f32 v[36:37], v[34:35], v[34:35]
	v_lshlrev_b32_e32 v30, 16, v31
	v_and_b32_e32 v31, 0xffff0000, v31
	v_pk_mul_f32 v[38:39], v[30:31], v[30:31]
	s_waitcnt lgkmcnt(0)
	v_add_f32_e32 v0, v36, v37
	v_lshlrev_b32_e32 v40, 16, v32
	v_and_b32_e32 v41, 0xffff0000, v32
	v_add_f32_e32 v0, v38, v0
	v_pk_mul_f32 v[66:67], v[40:41], v[40:41]
	v_add_f32_e32 v0, v39, v0
	v_lshlrev_b32_e32 v32, 16, v33
	v_and_b32_e32 v33, 0xffff0000, v33
	v_add_f32_e32 v0, v66, v0
	v_pk_mul_f32 v[68:69], v[32:33], v[32:33]
	v_add_f32_e32 v0, v67, v0
	v_add_f32_e32 v0, v68, v0
	v_add_f32_e32 v0, v69, v0
	s_nop 1
	v_add_f32_dpp v0, v0, v0 quad_perm:[1,0,3,2] row_mask:0xf bank_mask:0xf
	s_nop 1
	v_add_f32_dpp v0, v0, v0 quad_perm:[2,3,0,1] row_mask:0xf bank_mask:0xf
	s_nop 1
	v_add_f32_dpp v0, v0, v0 row_half_mirror row_mask:0xf bank_mask:0xf
	s_nop 1
	v_add_f32_dpp v0, v0, v0 row_mirror row_mask:0xf bank_mask:0xf
	s_nop 0
	v_fmamk_f32 v0, v0, 0x3c2aaaab, v193
	v_mul_f32_e32 v36, 0x4b800000, v0
	v_cmp_gt_f32_e32 vcc, s68, v0
	s_nop 1
	v_cndmask_b32_e32 v0, v0, v36, vcc
	v_rsq_f32_e32 v0, v0
	s_nop 0
	v_mul_f32_e32 v36, 0x45800000, v0
	v_cndmask_b32_e32 v0, v0, v36, vcc
	v_pk_mul_f32 v[34:35], v[0:1], v[34:35] op_sel_hi:[0,1]
	v_pk_mul_f32 v[30:31], v[0:1], v[30:31] op_sel_hi:[0,1]
	v_pk_mul_f32 v[38:39], v[0:1], v[40:41] op_sel_hi:[0,1]
	v_pk_mul_f32 v[40:41], v[0:1], v[32:33] op_sel_hi:[0,1]
	v_pk_mul_f32 v[32:33], v[6:7], v[34:35]
	v_pk_mul_f32 v[36:37], v[8:9], v[30:31]
	v_pk_mul_f32 v[38:39], v[2:3], v[38:39]
	v_pk_mul_f32 v[34:35], v[4:5], v[40:41]
	s_nop 1
	v_mov_b32_dpp v69, v32 quad_perm:[2,3,0,1] row_mask:0xf bank_mask:0xf
	v_mov_b32_dpp v68, v33 quad_perm:[2,3,0,1] row_mask:0xf bank_mask:0xf
	v_mov_b32_dpp v67, v36 quad_perm:[2,3,0,1] row_mask:0xf bank_mask:0xf
	v_mov_b32_dpp v66, v37 quad_perm:[2,3,0,1] row_mask:0xf bank_mask:0xf
	v_mov_b32_dpp v43, v38 quad_perm:[2,3,0,1] row_mask:0xf bank_mask:0xf
	v_mov_b32_dpp v41, v39 quad_perm:[2,3,0,1] row_mask:0xf bank_mask:0xf
	v_mov_b32_dpp v40, v34 quad_perm:[2,3,0,1] row_mask:0xf bank_mask:0xf
	v_mov_b32_dpp v0, v35 quad_perm:[2,3,0,1] row_mask:0xf bank_mask:0xf
	v_lshl_add_u64 v[30:31], v[60:61], 0, v[54:55]
	s_and_saveexec_b64 s[44:45], s[36:37]
	s_cbranch_execz .LBB0_736
; __device__ __forceinline__ u32x4 pack8(const float (&f)[8]) { u32x4 w; w.x = pk2(f[0], f[1]); w.y = pk2(f[2], f[3]); w.z = pk2(f[4], f[5]); w.w = pk2(f[6], f[7]); return w; }
; __device__ __forceinline__ void mla_phase(const Params& p, const WsMap& wm, const bf16_t* H, bf16_t* QC, bf16_t* KC, const bf16_t* KV, int Tc, int l) {
;     ...
;         for (int part = 0; part < 4; ++part) {
;             const int isk = part >> 1, h = (part & 1) * 4 + hl;
;             float f[8]; unpack8(w[part], f); float ss = 0.f;
; #pragma unroll
;             for (int i = 0; i < 8; ++i) ss += f[i] * f[i];
;             ss += __shfl_xor(ss, 1); ss += __shfl_xor(ss, 2); ss += __shfl_xor(ss, 4); ss += __shfl_xor(ss, 8);
;             const float rs = rsqrtf(ss * (1.0f / 96.0f) + 1e-6f);
; #pragma unroll
;             for (int i = 0; i < 8; ++i) f[i] = f[i] * rs * (isk ? gk[i] : gq[i]);
; #pragma unroll
;             for (int i = 0; i < 8; ++i) {
;                 const float other = __shfl_xor(f[i], 2);
;                 if (sub >= 8 && sub < 12) f[i] = (sub < 10) ? (f[i] * cc[i] - other * sn[i]) : (f[i] * cc[i] + other * sn[i]);
;             }
;             if (act) { bf16_t* dst = (isk ? KC : QC) + (size_t)row * 768 + h * 96 + sub * 8; *(u32x4*)dst = pack8(f); }
	s_waitcnt lgkmcnt(7)
	v_mul_f32_e32 v69, v26, v69
	s_waitcnt lgkmcnt(6)
	v_mul_f32_e32 v68, v27, v68
	s_waitcnt lgkmcnt(5)
	v_mul_f32_e32 v67, v28, v67
	v_cndmask_b32_e64 v69, v69, -v69, s[42:43]
	v_cndmask_b32_e64 v68, v68, -v68, s[42:43]
	v_cndmask_b32_e64 v67, v67, -v67, s[42:43]
	s_waitcnt lgkmcnt(4)
	v_mul_f32_e32 v66, v29, v66
	v_fmac_f32_e32 v69, v22, v32
	v_fmac_f32_e32 v68, v23, v33
	v_fmac_f32_e32 v67, v24, v36
	v_cndmask_b32_e64 v66, v66, -v66, s[42:43]
	s_waitcnt lgkmcnt(3)
	v_mul_f32_e32 v43, v18, v43
	s_waitcnt lgkmcnt(1)
	v_mul_f32_e32 v40, v20, v40
	v_fmac_f32_e32 v66, v25, v37
	v_cndmask_b32_e64 v43, v43, -v43, s[42:43]
	v_mul_f32_e32 v41, v19, v41
	v_cndmask_b32_e64 v40, v40, -v40, s[42:43]
	v_cndmask_b32_e64 v67, v36, v67, s[40:41]
	v_cndmask_b32_e64 v68, v33, v68, s[40:41]
	v_cndmask_b32_e64 v69, v32, v69, s[40:41]
	v_fmac_f32_e32 v43, v14, v38
	v_cndmask_b32_e64 v41, v41, -v41, s[42:43]
	v_fmac_f32_e32 v40, v16, v34
	v_cndmask_b32_e64 v66, v37, v66, s[40:41]
	s_waitcnt lgkmcnt(0)
	v_mul_f32_e32 v0, v21, v0
	v_cndmask_b32_e64 v36, v36, v67, s[40:41]
	v_cndmask_b32_e64 v32, v32, v69, s[40:41]
	v_cndmask_b32_e64 v33, v33, v68, s[40:41]
	v_fmac_f32_e32 v41, v15, v39
	v_cndmask_b32_e64 v40, v34, v40, s[40:41]
	v_cndmask_b32_e64 v43, v38, v43, s[40:41]
	v_cndmask_b32_e64 v0, v0, -v0, s[42:43]
	v_cndmask_b32_e64 v37, v37, v66, s[40:41]
	v_cvt_pk_bf16_f32 v32, v32, v33
	v_cvt_pk_bf16_f32 v33, v36, v37
	v_add_co_u32_e32 v36, vcc, 0xc8ca000, v30
	v_cndmask_b32_e64 v41, v39, v41, s[40:41]
	v_fmac_f32_e32 v0, v17, v35
	v_cndmask_b32_e64 v40, v34, v40, s[40:41]
	v_cndmask_b32_e64 v34, v38, v43, s[40:41]
	v_addc_co_u32_e32 v37, vcc, 0, v31, vcc
	v_cndmask_b32_e64 v38, v39, v41, s[40:41]
	v_cndmask_b32_e64 v0, v35, v0, s[40:41]
	v_cvt_pk_bf16_f32 v34, v34, v38
	v_cvt_pk_bf16_f32 v35, v40, v0
	global_store_dwordx4 v[36:37], v[32:35], off offset:256
.LBB0_736:
	s_or_b64 exec, exec, s[44:45]
	s_nop 0
	v_lshlrev_b32_e32 v32, 16, v10
	v_and_b32_e32 v33, 0xffff0000, v10
	v_pk_mul_f32 v[34:35], v[32:33], v[32:33]
	v_lshlrev_b32_e32 v10, 16, v11
	v_and_b32_e32 v11, 0xffff0000, v11
	v_pk_mul_f32 v[36:37], v[10:11], v[10:11]
	s_waitcnt lgkmcnt(0)
	v_add_f32_e32 v0, v34, v35
	v_lshlrev_b32_e32 v38, 16, v12
	v_and_b32_e32 v39, 0xffff0000, v12
	v_add_f32_e32 v0, v36, v0
	v_pk_mul_f32 v[40:41], v[38:39], v[38:39]
	v_add_f32_e32 v0, v37, v0
	v_lshlrev_b32_e32 v12, 16, v13
	v_and_b32_e32 v13, 0xffff0000, v13
	v_add_f32_e32 v0, v40, v0
	v_pk_mul_f32 v[66:67], v[12:13], v[12:13]
	v_add_f32_e32 v0, v41, v0
	v_add_f32_e32 v0, v66, v0
	v_add_f32_e32 v0, v67, v0
	s_nop 1
	v_add_f32_dpp v0, v0, v0 quad_perm:[1,0,3,2] row_mask:0xf bank_mask:0xf
	s_nop 1
	v_add_f32_dpp v0, v0, v0 quad_perm:[2,3,0,1] row_mask:0xf bank_mask:0xf
	s_nop 1
	v_add_f32_dpp v0, v0, v0 row_half_mirror row_mask:0xf bank_mask:0xf
	s_nop 1
	v_add_f32_dpp v0, v0, v0 row_mirror row_mask:0xf bank_mask:0xf
	s_nop 0
	v_fmamk_f32 v0, v0, 0x3c2aaaab, v193
	v_mul_f32_e32 v34, 0x4b800000, v0
	v_cmp_gt_f32_e32 vcc, s68, v0
	s_nop 1
	v_cndmask_b32_e32 v0, v0, v34, vcc
	v_rsq_f32_e32 v0, v0
	s_nop 0
	v_mul_f32_e32 v34, 0x45800000, v0
	v_cndmask_b32_e32 v0, v0, v34, vcc
	v_pk_mul_f32 v[32:33], v[0:1], v[32:33] op_sel_hi:[0,1]
	v_pk_mul_f32 v[34:35], v[0:1], v[10:11] op_sel_hi:[0,1]
	v_pk_mul_f32 v[36:37], v[0:1], v[38:39] op_sel_hi:[0,1]
	v_pk_mul_f32 v[12:13], v[0:1], v[12:13] op_sel_hi:[0,1]
	v_pk_mul_f32 v[10:11], v[6:7], v[32:33]
	v_pk_mul_f32 v[32:33], v[8:9], v[34:35]
	v_pk_mul_f32 v[34:35], v[2:3], v[36:37]
	v_pk_mul_f32 v[12:13], v[4:5], v[12:13]
	s_nop 1
	v_mov_b32_dpp v43, v10 quad_perm:[2,3,0,1] row_mask:0xf bank_mask:0xf
	v_mov_b32_dpp v41, v11 quad_perm:[2,3,0,1] row_mask:0xf bank_mask:0xf
	v_mov_b32_dpp v40, v32 quad_perm:[2,3,0,1] row_mask:0xf bank_mask:0xf
	v_mov_b32_dpp v39, v33 quad_perm:[2,3,0,1] row_mask:0xf bank_mask:0xf
	v_mov_b32_dpp v38, v34 quad_perm:[2,3,0,1] row_mask:0xf bank_mask:0xf
	v_mov_b32_dpp v37, v35 quad_perm:[2,3,0,1] row_mask:0xf bank_mask:0xf
	v_mov_b32_dpp v36, v12 quad_perm:[2,3,0,1] row_mask:0xf bank_mask:0xf
	v_mov_b32_dpp v0, v13 quad_perm:[2,3,0,1] row_mask:0xf bank_mask:0xf
	s_and_saveexec_b64 s[44:45], s[36:37]
	s_cbranch_execz .LBB0_713
	s_waitcnt lgkmcnt(7)
	v_mul_f32_e32 v26, v26, v43
	v_cndmask_b32_e64 v26, v26, -v26, s[42:43]
	s_waitcnt lgkmcnt(3)
	v_mul_f32_e32 v18, v18, v38
	v_fmac_f32_e32 v26, v22, v10
	v_mul_f32_e32 v22, v27, v41
	v_cndmask_b32_e64 v18, v18, -v18, s[42:43]
	v_cndmask_b32_e64 v22, v22, -v22, s[42:43]
	v_fmac_f32_e32 v18, v14, v34
	s_waitcnt lgkmcnt(2)
	v_mul_f32_e32 v14, v19, v37
	v_fmac_f32_e32 v22, v23, v11
	v_mul_f32_e32 v23, v28, v40
	v_cndmask_b32_e64 v14, v14, -v14, s[42:43]
	v_cndmask_b32_e64 v23, v23, -v23, s[42:43]
	v_fmac_f32_e32 v14, v15, v35
	s_waitcnt lgkmcnt(1)
	v_mul_f32_e32 v15, v20, v36
	v_fmac_f32_e32 v23, v24, v32
	v_mul_f32_e32 v24, v29, v39
	v_cndmask_b32_e64 v15, v15, -v15, s[42:43]
	v_cndmask_b32_e64 v24, v24, -v24, s[42:43]
	v_fmac_f32_e32 v15, v16, v12
	v_fmac_f32_e32 v24, v25, v33
	v_cndmask_b32_e64 v15, v12, v15, s[40:41]
	v_cndmask_b32_e64 v14, v35, v14, s[40:41]
	v_cndmask_b32_e64 v16, v34, v18, s[40:41]
	v_cndmask_b32_e64 v20, v11, v22, s[40:41]
	v_cndmask_b32_e64 v22, v10, v26, s[40:41]
	s_waitcnt lgkmcnt(0)
	v_mul_f32_e32 v0, v21, v0
	v_cndmask_b32_e64 v18, v33, v24, s[40:41]
	v_cndmask_b32_e64 v19, v32, v23, s[40:41]
	v_cndmask_b32_e64 v0, v0, -v0, s[42:43]
	v_cndmask_b32_e64 v15, v12, v15, s[40:41]
	v_cndmask_b32_e64 v12, v34, v16, s[40:41]
	v_cndmask_b32_e64 v14, v35, v14, s[40:41]
	v_cndmask_b32_e64 v10, v10, v22, s[40:41]
	v_cndmask_b32_e64 v11, v11, v20, s[40:41]
	v_fmac_f32_e32 v0, v17, v13
	v_cndmask_b32_e64 v16, v32, v19, s[40:41]
	v_cndmask_b32_e64 v17, v33, v18, s[40:41]
	v_cvt_pk_bf16_f32 v10, v10, v11
	v_cvt_pk_bf16_f32 v11, v16, v17
	v_cvt_pk_bf16_f32 v12, v12, v14
	v_add_co_u32_e32 v14, vcc, 0xc8ca000, v30
	v_cndmask_b32_e64 v0, v13, v0, s[40:41]
	v_cvt_pk_bf16_f32 v13, v15, v0
	s_nop 0
	v_addc_co_u32_e32 v15, vcc, 0, v31, vcc
	global_store_dwordx4 v[14:15], v[10:13], off offset:1024
	s_branch .LBB0_713
